# diff fast loop: step-B ring rotation / counters moved from the P.V shadows to behind the last P.V MFMA and the K.Q^T shadows
# baseline (speedup 1.0000x reference)
.Lfd_b_exp:
	v_exp_f32_e32 v80, v80
	v_exp_f32_e32 v96, v96
	v_exp_f32_e32 v81, v81
	v_exp_f32_e32 v97, v97
	v_exp_f32_e32 v88, v88
	v_exp_f32_e32 v104, v104
	v_exp_f32_e32 v89, v89
	v_exp_f32_e32 v105, v105
	v_exp_f32_e32 v82, v82
	v_exp_f32_e32 v98, v98
	v_exp_f32_e32 v83, v83
	v_exp_f32_e32 v99, v99
	v_exp_f32_e32 v90, v90
	v_exp_f32_e32 v106, v106
	v_exp_f32_e32 v91, v91
	v_exp_f32_e32 v107, v107
	v_exp_f32_e32 v84, v84
	v_exp_f32_e32 v100, v100
	v_exp_f32_e32 v85, v85
	v_exp_f32_e32 v101, v101
	v_exp_f32_e32 v92, v92
	v_exp_f32_e32 v108, v108
	v_exp_f32_e32 v93, v93
	v_exp_f32_e32 v109, v109
	v_exp_f32_e32 v86, v86
	v_exp_f32_e32 v102, v102
	v_exp_f32_e32 v87, v87
	v_exp_f32_e32 v103, v103
	v_exp_f32_e32 v94, v94
	v_exp_f32_e32 v110, v110
	v_exp_f32_e32 v95, v95
	v_exp_f32_e32 v111, v111
	v_pk_add_f32 v[140:141], v[80:81], v[96:97]
	v_pk_add_f32 v[142:143], v[82:83], v[98:99]
	v_pk_add_f32 v[144:145], v[84:85], v[100:101]
	v_pk_add_f32 v[146:147], v[86:87], v[102:103]
	v_pk_add_f32 v[148:149], v[88:89], v[104:105]
	v_pk_add_f32 v[150:151], v[90:91], v[106:107]
	v_pk_add_f32 v[152:153], v[92:93], v[108:109]
	v_pk_add_f32 v[154:155], v[94:95], v[110:111]
	v_pk_add_f32 v[140:141], v[140:141], v[142:143]
	v_pk_add_f32 v[144:145], v[144:145], v[146:147]
	v_pk_add_f32 v[148:149], v[148:149], v[150:151]
	v_pk_add_f32 v[152:153], v[152:153], v[154:155]
	v_pk_add_f32 v[140:141], v[140:141], v[144:145]
	v_pk_add_f32 v[148:149], v[148:149], v[152:153]
	v_pk_add_f32 v[140:141], v[140:141], v[148:149]
	v_add_f32_e32 v14, v140, v141
	v_cvt_pk_bf16_f32 v140, v80, v81
	v_cvt_pk_bf16_f32 v141, v82, v83
	v_cvt_pk_bf16_f32 v142, v84, v85
	v_cvt_pk_bf16_f32 v143, v86, v87
	v_cvt_pk_bf16_f32 v144, v88, v89
	v_cvt_pk_bf16_f32 v145, v90, v91
	v_cvt_pk_bf16_f32 v146, v92, v93
	v_cvt_pk_bf16_f32 v147, v94, v95
	v_cvt_pk_bf16_f32 v148, v96, v97
	v_cvt_pk_bf16_f32 v149, v98, v99
	v_cvt_pk_bf16_f32 v150, v100, v101
	v_cvt_pk_bf16_f32 v151, v102, v103
	v_cvt_pk_bf16_f32 v152, v104, v105
	v_cvt_pk_bf16_f32 v153, v106, v107
	v_cvt_pk_bf16_f32 v154, v108, v109
	v_cvt_pk_bf16_f32 v155, v110, v111
	v_add_f32_e32 v193, v193, v14
	s_waitcnt lgkmcnt(0)
	s_barrier
	v_mfma_f32_32x32x16_bf16 v[64:79], v[196:199], v[140:143], v[64:79]
	s_setprio 1
	v_add_u32_e32 v0, s51, v188
	s_waitcnt vmcnt(3)
	ds_write_b128 v0, v[10:13]
	v_mfma_f32_32x32x16_bf16 v[48:63], v[200:203], v[140:143], v[48:63]
	ds_read_b128 v[196:199], v248 offset:9280
	v_add_u32_e32 v0, s51, v186
	v_add_u32_e32 v10, v0, v175
	v_mfma_f32_32x32x16_bf16 v[32:47], v[204:207], v[140:143], v[32:47]
	ds_read_b128 v[200:203], v248 offset:13888
	v_add_u32_e32 v0, v0, v187
	ds_write_b128 v10, v[2:5] offset:9216
	v_mfma_f32_32x32x16_bf16 v[16:31], v[208:211], v[140:143], v[16:31]
	ds_read_b128 v[204:207], v248 offset:18496
	ds_write_b128 v0, v[6:9] offset:9216
	v_mfma_f32_32x32x16_bf16 v[64:79], v[212:215], v[144:147], v[64:79]
	ds_read_b128 v[208:211], v248 offset:23104
	v_add_u32_e32 v249, s50, v190
	v_mfma_f32_32x32x16_bf16 v[48:63], v[216:219], v[144:147], v[48:63]
	ds_read_b128 v[212:215], v248 offset:9312
	v_mfma_f32_32x32x16_bf16 v[32:47], v[220:223], v[144:147], v[32:47]
	ds_read_b128 v[216:219], v248 offset:13920
	v_mfma_f32_32x32x16_bf16 v[16:31], v[224:227], v[144:147], v[16:31]
	ds_read_b128 v[220:223], v248 offset:18528
	ds_read_b128 v[224:227], v248 offset:23136
	s_waitcnt lgkmcnt(4)
	v_mfma_f32_32x32x16_bf16 v[64:79], v[196:199], v[148:151], v[64:79]
	ds_read_b128 v[196:199], v249
	s_add_i32 s1, s54, 5
	s_lshl_b32 s8, s1, 6
	v_mfma_f32_32x32x16_bf16 v[48:63], v[200:203], v[148:151], v[48:63]
	ds_read_b128 v[200:203], v249 offset:4608
	v_add_u32_e32 v2, s8, v174
	v_ashrrev_i32_e32 v3, 31, v2
	v_mfma_f32_32x32x16_bf16 v[32:47], v[204:207], v[148:151], v[32:47]
	ds_read_b128 v[204:207], v249 offset:32
	v_lshlrev_b64 v[2:3], 10, v[2:3]
	v_lshl_add_u64 v[6:7], s[8:9], 1, v[176:177]
	v_mfma_f32_32x32x16_bf16 v[16:31], v[208:211], v[148:151], v[16:31]
	ds_read_b128 v[208:211], v249 offset:4640
	v_lshl_add_u64 v[2:3], v[182:183], 0, v[2:3]
	v_lshl_add_u64 v[4:5], v[6:7], 0, v[178:179]
	s_waitcnt lgkmcnt(4)
	v_mfma_f32_32x32x16_bf16 v[64:79], v[212:215], v[152:155], v[64:79]
	ds_read_b128 v[212:215], v249 offset:64
	v_lshl_add_u64 v[6:7], v[6:7], 0, v[180:181]
	global_load_dwordx4 v[10:13], v[2:3], off
	v_mfma_f32_32x32x16_bf16 v[48:63], v[216:219], v[152:155], v[48:63]
	ds_read_b128 v[216:219], v249 offset:4672
	s_nop 0
	global_load_dwordx4 v[2:5], v[4:5], off
	v_mfma_f32_32x32x16_bf16 v[32:47], v[220:223], v[152:155], v[32:47]
	ds_read_b128 v[220:223], v249 offset:96
	global_load_dwordx4 v[6:9], v[6:7], off
	v_mfma_f32_32x32x16_bf16 v[16:31], v[224:227], v[152:155], v[16:31]
	ds_read_b128 v[224:227], v249 offset:4704
	s_mov_b32 s0, s51
	s_mov_b32 s51, s50
	s_mov_b32 s50, s55
	s_mov_b32 s55, s0
	v_add_u32_e32 v248, s51, v190
	s_waitcnt lgkmcnt(4)
	v_mfma_f32_32x32x16_bf16 v[80:95], v[196:199], v[232:235], v[112:127]
	ds_read_b128 v[196:199], v248 offset:9216
	s_add_i32 s54, s54, 2
	v_mfma_f32_32x32x16_bf16 v[96:111], v[200:203], v[232:235], v[112:127]
	ds_read_b128 v[200:203], v248 offset:13824
	s_addk_i32 s47, 0x80
	v_mfma_f32_32x32x16_bf16 v[80:95], v[204:207], v[236:239], v[80:95]
	ds_read_b128 v[204:207], v248 offset:18432
	v_mfma_f32_32x32x16_bf16 v[96:111], v[208:211], v[236:239], v[96:111]
	ds_read_b128 v[208:211], v248 offset:23040
	s_waitcnt lgkmcnt(4)
	v_mfma_f32_32x32x16_bf16 v[80:95], v[212:215], v[240:243], v[80:95]
	ds_read_b128 v[212:215], v248 offset:9248
	v_mfma_f32_32x32x16_bf16 v[96:111], v[216:219], v[240:243], v[96:111]
	ds_read_b128 v[216:219], v248 offset:13856
	s_add_i32 s4, s48, s54
	v_mfma_f32_32x32x16_bf16 v[80:95], v[220:223], v[244:247], v[80:95]
	ds_read_b128 v[220:223], v248 offset:18464
	v_mfma_f32_32x32x16_bf16 v[96:111], v[224:227], v[244:247], v[96:111]
	ds_read_b128 v[224:227], v248 offset:23072
	s_cmp_lt_i32 s4, -1
	s_setprio 0
	s_waitcnt lgkmcnt(8)
	s_barrier
	s_cbranch_scc1 .Lfd_head
	s_mov_b32 s0, s51
	s_mov_b32 s51, s55
	s_branch .LBB0_1072
